# attention Q-latent fragments loaded at the start of top-k into registers dead during top-k, copied at attention setup
# baseline (speedup 1.0000x reference)
; __device__ __forceinline__ void attn_item(const Ptrs& P, unsigned char* lds, int b, int tq0, int tid) {
;     ...
;         volatile unsigned* xw = (volatile unsigned*)(lds + 147456);
;         const unsigned seq = (xw[32 + w] + 1u) & 0xffu; if (lane == 0) xw[32 + w] = seq;
;     ...
;         const bf16_t* qlp = P.QL + (rowb + tq) * 4096 + r16 * 256 + 8 * g;
; #pragma unroll
;         for (int ks = 0; ks < 8; ++ks) Af[ks] = *(const bf16x8*)(qlp + 32 * ks);
.LBB0_487:
	s_or_b64 exec, exec, s[12:13]
	s_lshl_b32 s83, s62, 2
	s_add_i32 s12, s83, 0
	s_add_i32 s20, s12, 0x24080
	v_mov_b64_e32 v[64:65], s[20:21]
	s_waitcnt lgkmcnt(0)
	s_barrier
	ds_read_b32 v64, v64
	s_waitcnt lgkmcnt(0)
	s_mov_b32 s95, 1
	v_add_u32_e32 v222, s65, v124
	v_add_u32_e32 v222, s81, v222
	v_mov_b32_e32 v223, 0
	v_lshlrev_b64 v[222:223], 13, v[222:223]
	v_lshl_add_u64 v[222:223], s[76:77], 0, v[222:223]
	v_mov_b32_e32 v224, v180
	v_mov_b32_e32 v225, 0
	v_lshl_add_u64 v[222:223], v[222:223], 0, v[224:225]
	v_lshlrev_b32_e32 v224, 1, v166
	v_lshl_add_u64 v[250:251], v[222:223], 0, v[224:225]
	global_load_dwordx4 v[160:163], v[250:251], off
	global_load_dwordx4 v[222:225], v[250:251], off offset:64
	global_load_dwordx4 v[226:229], v[250:251], off offset:128
	global_load_dwordx4 v[230:233], v[250:251], off offset:192
	global_load_dwordx4 v[234:237], v[250:251], off offset:256
	global_load_dwordx4 v[238:241], v[250:251], off offset:320
	global_load_dwordx4 v[242:245], v[250:251], off offset:384
	global_load_dwordx4 v[246:249], v[250:251], off offset:448
	s_nop 0
	s_nop 0
	s_nop 0
	s_nop 0
	s_nop 0
	s_nop 0
	v_add_u32_e32 v64, 1, v64
	v_and_b32_e32 v96, 0xff, v64
	s_and_saveexec_b64 s[12:13], s[4:5]
	s_cbranch_execz .LBB0_489
	v_mov_b64_e32 v[64:65], s[20:21]
	ds_write_b32 v64, v96
	s_waitcnt lgkmcnt(0)

; __device__ __forceinline__ void attn_item(const Ptrs& P, unsigned char* lds, int b, int tq0, int tid) {
;     ...
;     if (tmax < 256 || (DBG & 4)) {
;         for (int i = tid; i < 1024; i += 512) sel[i] = (unsigned short)(((i & 255) <= tq0 + (i >> 8)) ? (i & 255) : 0);
;         __syncthreads();
.LBB0_913:
	s_or_saveexec_b64 s[14:15], s[60:61]
	v_mov_b32_e32 v32, s65
	v_mov_b32_e32 v219, s64
	s_xor_b64 exec, exec, s[14:15]
	s_cbranch_execz .LBB0_921
	s_and_saveexec_b64 s[90:91], s[0:1]
	v_mov_b32_e32 v0, 0x24108
	v_mov_b32_e32 v1, 0xffff
	ds_write_b32 v0, v1
	s_mov_b64 exec, s[90:91]
	s_mov_b32 s95, 0
	s_nop 0
	s_nop 0
	s_nop 0
	s_nop 0
	s_nop 0
	s_nop 0
	s_nop 0
	s_nop 0
	s_nop 0
	s_nop 0
	s_nop 0
	s_nop 0
	v_sub_u32_e32 v0, v208, v64
	v_sub_u32_e32 v1, v210, v64
	s_mov_b32 s18, 0
	s_mov_b64 s[16:17], 0
	v_mov_b32_e32 v2, v209
	s_branch .LBB0_916

; __device__ __forceinline__ void attn_item(const Ptrs& P, unsigned char* lds, int b, int tq0, int tid) {
;     ...
;         const bf16_t* qlp = P.QL + (rowb + tq) * 4096 + r16 * 256 + 8 * g;
; #pragma unroll
;         for (int ks = 0; ks < 8; ++ks) Af[ks] = *(const bf16x8*)(qlp + 32 * ks);
;     }
;     bf16_t* stw = stg + w * 32 * SP;
;     bf16_t* Pw = (bf16_t*)(l2 + 2048) + w * 16 * 40;
;     volatile unsigned* xa = (volatile unsigned*)(lds + 147456);
;     const unsigned aseq = (xa[40 + w] + 1u) & 0xffffu; if (lane == 0) xa[40 + w] = aseq;
.LBB0_921:
	s_or_b64 exec, exec, s[14:15]
	v_add_u32_e32 v220, v32, v124
	v_add_u32_e32 v164, s81, v220
	v_lshlrev_b64 v[0:1], 13, v[164:165]
	v_lshl_add_u64 v[184:185], s[76:77], 0, v[0:1]
	v_mov_b32_e32 v181, v165
	v_lshl_add_u64 v[0:1], v[184:185], 0, v[180:181]
	v_lshlrev_b32_e32 v164, 1, v166
	v_lshl_add_u64 v[28:29], v[0:1], 0, v[164:165]
	s_cmp_eq_u32 s95, 1
	s_cbranch_scc1 .Lql_skip
	global_load_dwordx4 v[0:3], v[28:29], off
	global_load_dwordx4 v[4:7], v[28:29], off offset:64
	global_load_dwordx4 v[8:11], v[28:29], off offset:128
	global_load_dwordx4 v[12:15], v[28:29], off offset:192
	global_load_dwordx4 v[16:19], v[28:29], off offset:256
	global_load_dwordx4 v[20:23], v[28:29], off offset:320
	global_load_dwordx4 v[24:27], v[28:29], off offset:384
	s_nop 0
	global_load_dwordx4 v[28:31], v[28:29], off offset:448
.Lql_skip:
	s_lshl_b32 s12, s62, 2
	s_add_i32 s16, s12, 0
	s_add_i32 s20, s16, 0x240a0
	v_mov_b64_e32 v[34:35], s[20:21]
	ds_read_b32 v33, v34
	s_waitcnt vmcnt(0) lgkmcnt(0)
	s_cmp_eq_u32 s95, 1
	s_cbranch_scc0 .Lql_nocopy
	v_mov_b32_e32 v0, v160
	v_mov_b32_e32 v1, v161
	v_mov_b32_e32 v2, v162
	v_mov_b32_e32 v3, v163
	v_mov_b32_e32 v4, v222
	v_mov_b32_e32 v5, v223
	v_mov_b32_e32 v6, v224
	v_mov_b32_e32 v7, v225
	v_mov_b32_e32 v8, v226
	v_mov_b32_e32 v9, v227
	v_mov_b32_e32 v10, v228
	v_mov_b32_e32 v11, v229
	v_mov_b32_e32 v12, v230
	v_mov_b32_e32 v13, v231
	v_mov_b32_e32 v14, v232
	v_mov_b32_e32 v15, v233
	v_mov_b32_e32 v16, v234
	v_mov_b32_e32 v17, v235
	v_mov_b32_e32 v18, v236
	v_mov_b32_e32 v19, v237
	v_mov_b32_e32 v20, v238
	v_mov_b32_e32 v21, v239
	v_mov_b32_e32 v22, v240
	v_mov_b32_e32 v23, v241
	v_mov_b32_e32 v24, v242
	v_mov_b32_e32 v25, v243
	v_mov_b32_e32 v26, v244
	v_mov_b32_e32 v27, v245
	v_mov_b32_e32 v28, v246
	v_mov_b32_e32 v29, v247
	v_mov_b32_e32 v30, v248
	v_mov_b32_e32 v31, v249
.Lql_nocopy:
	s_nop 0
	s_nop 0
	s_nop 0
	s_nop 0
	s_nop 0
	s_nop 0
	s_nop 0
	s_nop 0
	s_nop 0
	s_nop 0
	s_nop 0
	s_nop 0
	v_add_u32_e32 v33, 1, v33
	v_and_b32_e32 v218, 0xffff, v33
	s_and_saveexec_b64 s[12:13], s[4:5]
	s_cbranch_execz .LBB0_923
	v_mov_b64_e32 v[34:35], s[20:21]
	ds_write_b32 v34, v218
	s_waitcnt vmcnt(0) lgkmcnt(0)
